# D3 state wave: hand-off flag write under s_mov exec,1 instead of saveexec + execz branch (loop-edge edit on the serial chain between the two MFMA groups)
# speedup vs baseline: 1.0007x; 1.0007x over previous
; #define LAS __attribute__((address_space(3)))
; #define MFMA32(a, b, c) __builtin_amdgcn_mfma_f32_32x32x16_bf16((a), (b), (c), 0, 0, 0)
; DI float bflo(unsigned u) { return __uint_as_float(u << 16); }
; DI float bfhi(unsigned u) { return __uint_as_float(u & 0xffff0000u); }
; DI void d3_block(const Params& P, int bh, int vs, LAS unsigned char* lds, int wave, int lane, int tid) {
;     ...
;         for (int n = 0; n < 128; ++n) {
;             const LAS unsigned char* sb = lds + (n & 1) * D3_SLOT;
;             const LAS bf16x8* fNW = (const LAS bf16x8*)sb + lane; const LAS bf16x8* fKD = (const LAS bf16x8*)(sb + 40960) + lane;
;             const LAS u32x4* fU = (const LAS u32x4*)(sb + 57344) + lane * 2;
;             const float gl_next = GL[(n + 1) & 127];
;             bf16x8 fw[16];
; #pragma unroll
;             for (int q = 0; q < 16; ++q) fw[q] = fNW[q * 64];
;             f32x16 vt[2];
; #pragma unroll
;             for (int t = 0; t < 2; ++t) { const u32x4 a = fU[t * 128], b2 = fU[t * 128 + 1];
;                 vt[t][0] = bflo(a.x); vt[t][1] = bfhi(a.x); vt[t][2] = bflo(a.y); vt[t][3] = bfhi(a.y); vt[t][4] = bflo(a.z); vt[t][5] = bfhi(a.z); vt[t][6] = bflo(a.w); vt[t][7] = bfhi(a.w);
;                 vt[t][8] = bflo(b2.x); vt[t][9] = bfhi(b2.x); vt[t][10] = bflo(b2.y); vt[t][11] = bfhi(b2.y); vt[t][12] = bflo(b2.z); vt[t][13] = bfhi(b2.z); vt[t][14] = bflo(b2.w); vt[t][15] = bfhi(b2.w); }
;             __builtin_amdgcn_sched_barrier(0);
; #pragma unroll
;             for (int G = 0; G < 8; ++G) {
;                 vt[0] = MFMA32(fw[G], Sb[G], vt[0]); vt[1] = MFMA32(fw[8 + G], Sb[G], vt[1]);
;                 if (G < 4) {
; #pragma unroll
;                     for (int i = 0; i < 16; ++i) S[G][i] *= gl; } }
;             __builtin_amdgcn_sched_barrier(0);
;             bf16x8 fk[16];
; #pragma unroll
;             for (int q = 0; q < 16; ++q) fk[q] = fKD[q * 64];
;             __builtin_amdgcn_sched_barrier(0);
;             bf16x8 Vb[4];
;             Vb[0] = pack8(vt[0], 0); Vb[1] = pack8(vt[0], 1); Vb[2] = pack8(vt[1], 0); Vb[3] = pack8(vt[1], 1);
; #pragma unroll
;             for (int G = 0; G < 4; ++G) exVb[G * 64] = Vb[G];
;             asm volatile("s_waitcnt lgkmcnt(0)" ::: "memory");
;             if (lane == 0) *vflag = (unsigned)(n + 1);
.LBB0_369:
	s_bitcmp1_b32 s8, 0
	s_cselect_b32 s4, 0xf000, 0
	s_add_i32 s8, s8, 1
	s_and_b32 s5, s8, 0x7f
	s_lshl_b32 s5, s5, 2
	v_mov_b32_e32 v64, s5
	global_load_dword v170, v64, s[0:1]
	s_add_i32 s4, s4, 0
	v_lshl_add_u32 v64, v240, 4, s4
	ds_read_b128 v[130:133], v64
	ds_read_b128 v[134:137], v64 offset:1024
	ds_read_b128 v[138:141], v64 offset:2048
	ds_read_b128 v[142:145], v64 offset:3072
	ds_read_b128 v[146:149], v64 offset:4096
	ds_read_b128 v[150:153], v64 offset:5120
	ds_read_b128 v[154:157], v64 offset:6144
	ds_read_b128 v[158:161], v64 offset:7168
	ds_read_b128 v[162:165], v64 offset:8192
	ds_read_b128 v[172:175], v64 offset:9216
	ds_read_b128 v[176:179], v64 offset:10240
	ds_read_b128 v[184:187], v64 offset:11264
	v_add_u32_e32 v171, s4, v168
	ds_read_b128 v[68:71], v171 offset:57344
	ds_read_b128 v[196:199], v64 offset:12288
	ds_read_b128 v[200:203], v64 offset:13312
	ds_read_b128 v[204:207], v64 offset:14336
	ds_read_b128 v[208:211], v64 offset:15360
	ds_read_b128 v[76:79], v171 offset:57360
	ds_read_b128 v[84:87], v171 offset:59392
	ds_read_b128 v[92:95], v171 offset:59408
	s_waitcnt lgkmcnt(0)
	v_lshlrev_b32_e32 v64, 16, v68
	v_and_b32_e32 v65, 0xffff0000, v68
	v_lshlrev_b32_e32 v66, 16, v69
	v_and_b32_e32 v67, 0xffff0000, v69
	v_lshlrev_b32_e32 v68, 16, v70
	v_and_b32_e32 v69, 0xffff0000, v70
	v_lshlrev_b32_e32 v70, 16, v71
	v_and_b32_e32 v71, 0xffff0000, v71
	v_lshlrev_b32_e32 v72, 16, v76
	v_and_b32_e32 v73, 0xffff0000, v76
	v_lshlrev_b32_e32 v74, 16, v77
	v_and_b32_e32 v75, 0xffff0000, v77
	v_lshlrev_b32_e32 v76, 16, v78
	v_and_b32_e32 v77, 0xffff0000, v78
	v_lshlrev_b32_e32 v78, 16, v79
	v_and_b32_e32 v79, 0xffff0000, v79
	v_lshlrev_b32_e32 v80, 16, v84
	v_and_b32_e32 v81, 0xffff0000, v84
	v_lshlrev_b32_e32 v82, 16, v85
	v_and_b32_e32 v83, 0xffff0000, v85
	v_lshlrev_b32_e32 v84, 16, v86
	v_and_b32_e32 v85, 0xffff0000, v86
	v_lshlrev_b32_e32 v86, 16, v87
	v_and_b32_e32 v87, 0xffff0000, v87
	v_lshlrev_b32_e32 v88, 16, v92
	v_and_b32_e32 v89, 0xffff0000, v92
	v_lshlrev_b32_e32 v90, 16, v93
	v_and_b32_e32 v91, 0xffff0000, v93
	v_lshlrev_b32_e32 v92, 16, v94
	v_and_b32_e32 v93, 0xffff0000, v94
	v_lshlrev_b32_e32 v94, 16, v95
	v_and_b32_e32 v95, 0xffff0000, v95
	v_mfma_f32_32x32x16_bf16 v[64:79], v[130:133], v[98:101], v[64:79]
	v_mul_f32_e32 v0, v96, v0
	v_mul_f32_e32 v1, v96, v1
	v_mul_f32_e32 v2, v96, v2
	v_mul_f32_e32 v3, v96, v3
	v_mfma_f32_32x32x16_bf16 v[80:95], v[162:165], v[98:101], v[80:95]
	v_mul_f32_e32 v4, v96, v4
	v_mul_f32_e32 v5, v96, v5
	v_mul_f32_e32 v6, v96, v6
	v_mul_f32_e32 v7, v96, v7
	v_mfma_f32_32x32x16_bf16 v[64:79], v[134:137], v[102:105], v[64:79]
	v_mul_f32_e32 v8, v96, v8
	v_mul_f32_e32 v9, v96, v9
	v_mul_f32_e32 v10, v96, v10
	v_mul_f32_e32 v11, v96, v11
	v_mfma_f32_32x32x16_bf16 v[80:95], v[172:175], v[102:105], v[80:95]
	v_mul_f32_e32 v12, v96, v12
	v_mul_f32_e32 v13, v96, v13
	v_mul_f32_e32 v14, v96, v14
	v_mul_f32_e32 v15, v96, v15
	v_mfma_f32_32x32x16_bf16 v[64:79], v[138:141], v[106:109], v[64:79]
	v_mul_f32_e32 v16, v96, v16
	v_mul_f32_e32 v17, v96, v17
	v_mul_f32_e32 v18, v96, v18
	v_mul_f32_e32 v19, v96, v19
	v_mfma_f32_32x32x16_bf16 v[80:95], v[176:179], v[106:109], v[80:95]
	v_mul_f32_e32 v20, v96, v20
	v_mul_f32_e32 v21, v96, v21
	v_mul_f32_e32 v22, v96, v22
	v_mul_f32_e32 v23, v96, v23
	v_mfma_f32_32x32x16_bf16 v[64:79], v[142:145], v[110:113], v[64:79]
	v_mul_f32_e32 v24, v96, v24
	v_mul_f32_e32 v25, v96, v25
	v_mul_f32_e32 v26, v96, v26
	v_mul_f32_e32 v27, v96, v27
	v_mfma_f32_32x32x16_bf16 v[80:95], v[184:187], v[110:113], v[80:95]
	v_mul_f32_e32 v28, v96, v28
	v_mul_f32_e32 v29, v96, v29
	v_mul_f32_e32 v30, v96, v30
	v_mul_f32_e32 v31, v96, v31
	v_add_u32_e32 v110, v171, v169
	v_mfma_f32_32x32x16_bf16 v[64:79], v[146:149], v[114:117], v[64:79]
	v_mul_f32_e32 v32, v96, v32
	v_mul_f32_e32 v33, v96, v33
	v_mul_f32_e32 v34, v96, v34
	v_mul_f32_e32 v35, v96, v35
	v_mfma_f32_32x32x16_bf16 v[80:95], v[196:199], v[114:117], v[80:95]
	v_mul_f32_e32 v36, v96, v36
	v_mul_f32_e32 v37, v96, v37
	v_mul_f32_e32 v38, v96, v38
	v_mul_f32_e32 v39, v96, v39
	v_mfma_f32_32x32x16_bf16 v[64:79], v[150:153], v[118:121], v[64:79]
	v_mul_f32_e32 v40, v96, v40
	v_mul_f32_e32 v41, v96, v41
	v_mul_f32_e32 v42, v96, v42
	v_mul_f32_e32 v43, v96, v43
	v_mfma_f32_32x32x16_bf16 v[80:95], v[200:203], v[118:121], v[80:95]
	v_mul_f32_e32 v44, v96, v44
	v_mul_f32_e32 v45, v96, v45
	v_mul_f32_e32 v46, v96, v46
	v_mul_f32_e32 v47, v96, v47
	v_mfma_f32_32x32x16_bf16 v[64:79], v[154:157], v[122:125], v[64:79]
	v_mul_f32_e32 v48, v96, v48
	v_mul_f32_e32 v49, v96, v49
	v_mul_f32_e32 v50, v96, v50
	v_mul_f32_e32 v51, v96, v51
	v_mfma_f32_32x32x16_bf16 v[80:95], v[204:207], v[122:125], v[80:95]
	v_mul_f32_e32 v52, v96, v52
	v_mul_f32_e32 v53, v96, v53
	v_mul_f32_e32 v54, v96, v54
	v_mul_f32_e32 v55, v96, v55
	v_mfma_f32_32x32x16_bf16 v[64:79], v[158:161], v[126:129], v[64:79]
	v_mul_f32_e32 v56, v96, v56
	v_mul_f32_e32 v57, v96, v57
	v_mul_f32_e32 v58, v96, v58
	v_mul_f32_e32 v59, v96, v59
	v_mfma_f32_32x32x16_bf16 v[80:95], v[208:211], v[126:129], v[80:95]
	v_mul_f32_e32 v60, v96, v60
	v_mul_f32_e32 v61, v96, v61
	v_mul_f32_e32 v62, v96, v62
	v_mul_f32_e32 v63, v96, v63
	ds_read_b128 v[162:165], v110 offset:40960
	ds_read_b128 v[130:133], v110 offset:41984
	ds_read_b128 v[114:117], v110 offset:43008
	ds_read_b128 v[98:101], v110 offset:44032
	ds_read_b128 v[158:161], v110 offset:45056
	ds_read_b128 v[134:137], v110 offset:46080
	ds_read_b128 v[118:121], v110 offset:47104
	ds_read_b128 v[102:105], v110 offset:48128
	ds_read_b128 v[150:153], v110 offset:49152
	ds_read_b128 v[138:141], v110 offset:50176
	ds_read_b128 v[122:125], v110 offset:51200
	ds_read_b128 v[106:109], v110 offset:52224
	ds_read_b128 v[146:149], v110 offset:53248
	ds_read_b128 v[142:145], v110 offset:54272
	ds_read_b128 v[126:129], v110 offset:55296
	ds_read_b128 v[110:113], v110 offset:56320
	v_cvt_pk_bf16_f32 v154, v64, v65
	v_cvt_pk_bf16_f32 v155, v66, v67
	v_cvt_pk_bf16_f32 v156, v68, v69
	v_cvt_pk_bf16_f32 v157, v70, v71
	v_cvt_pk_bf16_f32 v72, v72, v73
	v_cvt_pk_bf16_f32 v73, v74, v75
	v_cvt_pk_bf16_f32 v74, v76, v77
	v_cvt_pk_bf16_f32 v75, v78, v79
	v_cvt_pk_bf16_f32 v68, v80, v81
	v_cvt_pk_bf16_f32 v69, v82, v83
	v_cvt_pk_bf16_f32 v70, v84, v85
	v_cvt_pk_bf16_f32 v71, v86, v87
	v_cvt_pk_bf16_f32 v64, v88, v89
	v_cvt_pk_bf16_f32 v65, v90, v91
	v_cvt_pk_bf16_f32 v66, v92, v93
	v_cvt_pk_bf16_f32 v67, v94, v95
	ds_write_b128 v167, v[154:157]
	ds_write_b128 v167, v[72:75] offset:1024
	ds_write_b128 v167, v[68:71] offset:2048
	ds_write_b128 v167, v[64:67] offset:3072
	s_waitcnt lgkmcnt(0)
	s_mov_b64 s[4:5], exec
	s_mov_b64 exec, 1
	v_readlane_b32 s9, v254, 21
	v_mov_b32_e32 v77, s8
	s_nop 0
	v_mov_b32_e32 v76, s9
	ds_write_b32 v76, v77
	s_mov_b64 exec, s[4:5]
	s_branch .LBB0_368
